# v11: v9 plus write-through (sc1) 16-byte stores for the in-projection GEMM outputs of layers 0-2
# baseline (speedup 1.0000x reference)
.LBB0_284:
	s_lshl_b32 s0, s28, 8
	s_add_i32 s0, s0, s47
	v_add_u32_e32 v170, s0, v162
	v_mov_b32_e32 v164, v170
	v_lshlrev_b64 v[154:155], 2, v[154:155]
	v_ashrrev_i32_e32 v165, 31, v164
	v_lshlrev_b64 v[164:165], 6, v[164:165]
	v_lshl_add_u64 v[164:165], s[10:11], 0, v[164:165]
	v_lshl_add_u64 v[168:169], v[164:165], 0, v[154:155]
	s_waitcnt vmcnt(0)
	v_pk_add_f32 v[166:167], v[128:129], v[132:133]
	v_pk_add_f32 v[164:165], v[126:127], v[130:131]
	flat_store_dwordx4 v[168:169], v[164:167] sc1
	s_nop 1
	v_pk_add_f32 v[166:167], v[124:125], v[136:137]
	v_pk_add_f32 v[164:165], v[122:123], v[134:135]
	flat_store_dwordx4 v[168:169], v[164:167] offset:16 sc1
	s_nop 1
	v_add_u32_e32 v164, 16, v170
	v_pk_add_f32 v[166:167], v[120:121], v[132:133]
	v_ashrrev_i32_e32 v165, 31, v164
	v_lshlrev_b64 v[164:165], 6, v[164:165]
	v_lshl_add_u64 v[164:165], s[10:11], 0, v[164:165]
	v_lshl_add_u64 v[168:169], v[164:165], 0, v[154:155]
	v_pk_add_f32 v[164:165], v[118:119], v[130:131]
	flat_store_dwordx4 v[168:169], v[164:167] sc1
	s_nop 1
	v_pk_add_f32 v[166:167], v[112:113], v[136:137]
	v_pk_add_f32 v[164:165], v[110:111], v[134:135]
	flat_store_dwordx4 v[168:169], v[164:167] offset:16 sc1
	s_nop 1
	v_add_u32_e32 v164, 32, v170
	v_pk_add_f32 v[166:167], v[104:105], v[132:133]
	v_ashrrev_i32_e32 v165, 31, v164
	v_lshlrev_b64 v[164:165], 6, v[164:165]
	v_lshl_add_u64 v[164:165], s[10:11], 0, v[164:165]
	v_lshl_add_u64 v[168:169], v[164:165], 0, v[154:155]
	v_pk_add_f32 v[164:165], v[102:103], v[130:131]
	flat_store_dwordx4 v[168:169], v[164:167] sc1
	s_nop 1
	v_pk_add_f32 v[166:167], v[96:97], v[136:137]
	v_pk_add_f32 v[164:165], v[94:95], v[134:135]
	flat_store_dwordx4 v[168:169], v[164:167] offset:16 sc1
	s_nop 1
	v_add_u32_e32 v164, 48, v170
	v_pk_add_f32 v[166:167], v[88:89], v[132:133]
	v_ashrrev_i32_e32 v165, 31, v164
	v_lshlrev_b64 v[164:165], 6, v[164:165]
	v_lshl_add_u64 v[164:165], s[10:11], 0, v[164:165]
	v_lshl_add_u64 v[168:169], v[164:165], 0, v[154:155]
	v_pk_add_f32 v[164:165], v[86:87], v[130:131]
	flat_store_dwordx4 v[168:169], v[164:167] sc1
	s_nop 1
	v_pk_add_f32 v[166:167], v[80:81], v[136:137]
	v_pk_add_f32 v[164:165], v[78:79], v[134:135]
	flat_store_dwordx4 v[168:169], v[164:167] offset:16 sc1
	s_nop 1
	v_add_u32_e32 v164, 0x80, v170
	v_pk_add_f32 v[166:167], v[64:65], v[132:133]
	v_ashrrev_i32_e32 v165, 31, v164
	v_lshlrev_b64 v[164:165], 6, v[164:165]
	v_lshl_add_u64 v[164:165], s[10:11], 0, v[164:165]
	v_lshl_add_u64 v[168:169], v[164:165], 0, v[154:155]
	v_pk_add_f32 v[164:165], v[62:63], v[130:131]
	flat_store_dwordx4 v[168:169], v[164:167] sc1
	s_nop 1
	v_pk_add_f32 v[166:167], v[60:61], v[136:137]
	v_pk_add_f32 v[164:165], v[58:59], v[134:135]
	flat_store_dwordx4 v[168:169], v[164:167] offset:16 sc1
	s_nop 1
	v_add_u32_e32 v164, 0x90, v170
	v_pk_add_f32 v[166:167], v[56:57], v[132:133]
	v_ashrrev_i32_e32 v165, 31, v164
	v_lshlrev_b64 v[164:165], 6, v[164:165]
	v_lshl_add_u64 v[164:165], s[10:11], 0, v[164:165]
	v_lshl_add_u64 v[168:169], v[164:165], 0, v[154:155]
	v_pk_add_f32 v[164:165], v[54:55], v[130:131]
	flat_store_dwordx4 v[168:169], v[164:167] sc1
	s_nop 1
	v_pk_add_f32 v[166:167], v[48:49], v[136:137]
	v_pk_add_f32 v[164:165], v[46:47], v[134:135]
	flat_store_dwordx4 v[168:169], v[164:167] offset:16 sc1
	s_nop 1
	v_add_u32_e32 v164, 0xa0, v170
	v_pk_add_f32 v[166:167], v[40:41], v[132:133]
	v_ashrrev_i32_e32 v165, 31, v164
	v_lshlrev_b64 v[164:165], 6, v[164:165]
	v_lshl_add_u64 v[164:165], s[10:11], 0, v[164:165]
	v_lshl_add_u64 v[168:169], v[164:165], 0, v[154:155]
	v_pk_add_f32 v[164:165], v[38:39], v[130:131]
	flat_store_dwordx4 v[168:169], v[164:167] sc1
	v_pk_add_f32 v[132:133], v[24:25], v[132:133]
	v_pk_add_f32 v[130:131], v[22:23], v[130:131]
	v_pk_add_f32 v[166:167], v[32:33], v[136:137]
	v_pk_add_f32 v[164:165], v[30:31], v[134:135]
	flat_store_dwordx4 v[168:169], v[164:167] offset:16 sc1
	s_nop 1
	v_add_u32_e32 v164, 0xb0, v170
	s_nop 0
	v_ashrrev_i32_e32 v165, 31, v164
	v_lshlrev_b64 v[164:165], 6, v[164:165]
	v_lshl_add_u64 v[164:165], s[10:11], 0, v[164:165]
	v_lshl_add_u64 v[154:155], v[164:165], 0, v[154:155]
	flat_store_dwordx4 v[154:155], v[130:133] sc1
	s_nop 1
	v_pk_add_f32 v[132:133], v[16:17], v[136:137]
	v_pk_add_f32 v[130:131], v[14:15], v[134:135]
	flat_store_dwordx4 v[154:155], v[130:133] offset:16 sc1

.LBB0_286:
	s_andn2_b64 vcc, exec, s[30:31]
	s_cbranch_vccnz .LBB0_274
	s_lshl_b32 s0, s55, 8
	s_or_b32 s0, s0, s48
	s_cmp_lt_i32 s55, 2
	v_lshl_add_u32 v132, v163, 3, s0
	s_cselect_b64 vcc, -1, 0
	s_lshl_b32 s0, s28, 8
	s_add_i32 s0, s0, s47
	v_add_u32_e32 v131, s0, v162
	v_cndmask_b32_e32 v130, 1.0, v161, vcc
	v_ashrrev_i32_e32 v133, 31, v132
	v_mov_b32_e32 v134, v131
	v_lshl_add_u64 v[132:133], v[132:133], 1, s[14:15]
	v_pk_mul_f32 v[128:129], v[130:131], v[128:129] op_sel_hi:[0,1]
	v_pk_mul_f32 v[126:127], v[130:131], v[126:127] op_sel_hi:[0,1]
	v_pk_mul_f32 v[136:137], v[130:131], v[124:125] op_sel_hi:[0,1]
	v_pk_mul_f32 v[124:125], v[130:131], v[122:123] op_sel_hi:[0,1]
	v_mad_i64_i32 v[134:135], s[0:1], v134, s54, v[132:133]
	v_cvt_pk_bf16_f32 v122, v126, v127
	v_cvt_pk_bf16_f32 v123, v128, v129
	v_cvt_pk_bf16_f32 v124, v124, v125
	v_cvt_pk_bf16_f32 v125, v136, v137
	flat_store_dwordx4 v[134:135], v[122:125] sc1
	v_pk_mul_f32 v[116:117], v[130:131], v[116:117] op_sel_hi:[0,1]
	v_pk_mul_f32 v[114:115], v[130:131], v[114:115] op_sel_hi:[0,1]
	v_pk_mul_f32 v[122:123], v[130:131], v[108:109] op_sel_hi:[0,1]
	v_pk_mul_f32 v[108:109], v[130:131], v[106:107] op_sel_hi:[0,1]
	v_cvt_pk_bf16_f32 v106, v114, v115
	v_cvt_pk_bf16_f32 v107, v116, v117
	v_cvt_pk_bf16_f32 v108, v108, v109
	v_cvt_pk_bf16_f32 v109, v122, v123
	flat_store_dwordx4 v[134:135], v[106:109] offset:256 sc1
	v_pk_mul_f32 v[112:113], v[130:131], v[112:113] op_sel_hi:[0,1]
	v_pk_mul_f32 v[110:111], v[130:131], v[110:111] op_sel_hi:[0,1]
	v_add_u32_e32 v106, 16, v131
	v_pk_mul_f32 v[108:109], v[130:131], v[120:121] op_sel_hi:[0,1]
	v_mad_i64_i32 v[114:115], s[0:1], v106, s54, v[132:133]
	v_pk_mul_f32 v[106:107], v[130:131], v[118:119] op_sel_hi:[0,1]
	v_cvt_pk_bf16_f32 v106, v106, v107
	v_cvt_pk_bf16_f32 v107, v108, v109
	v_cvt_pk_bf16_f32 v108, v110, v111
	v_cvt_pk_bf16_f32 v109, v112, v113
	flat_store_dwordx4 v[114:115], v[106:109] sc1
	v_pk_mul_f32 v[100:101], v[130:131], v[100:101] op_sel_hi:[0,1]
	v_pk_mul_f32 v[98:99], v[130:131], v[98:99] op_sel_hi:[0,1]
	v_pk_mul_f32 v[106:107], v[130:131], v[92:93] op_sel_hi:[0,1]
	v_pk_mul_f32 v[92:93], v[130:131], v[90:91] op_sel_hi:[0,1]
	v_cvt_pk_bf16_f32 v90, v98, v99
	v_cvt_pk_bf16_f32 v91, v100, v101
	v_cvt_pk_bf16_f32 v92, v92, v93
	v_cvt_pk_bf16_f32 v93, v106, v107
	flat_store_dwordx4 v[114:115], v[90:93] offset:256 sc1
	v_pk_mul_f32 v[96:97], v[130:131], v[96:97] op_sel_hi:[0,1]
	v_pk_mul_f32 v[94:95], v[130:131], v[94:95] op_sel_hi:[0,1]
	v_add_u32_e32 v90, 32, v131
	v_pk_mul_f32 v[92:93], v[130:131], v[104:105] op_sel_hi:[0,1]
	v_mad_i64_i32 v[98:99], s[0:1], v90, s54, v[132:133]
	v_pk_mul_f32 v[90:91], v[130:131], v[102:103] op_sel_hi:[0,1]
	v_cvt_pk_bf16_f32 v90, v90, v91
	v_cvt_pk_bf16_f32 v91, v92, v93
	v_cvt_pk_bf16_f32 v92, v94, v95
	v_cvt_pk_bf16_f32 v93, v96, v97
	flat_store_dwordx4 v[98:99], v[90:93] sc1
	v_pk_mul_f32 v[84:85], v[130:131], v[84:85] op_sel_hi:[0,1]
	v_pk_mul_f32 v[82:83], v[130:131], v[82:83] op_sel_hi:[0,1]
	v_pk_mul_f32 v[90:91], v[130:131], v[76:77] op_sel_hi:[0,1]
	v_pk_mul_f32 v[76:77], v[130:131], v[74:75] op_sel_hi:[0,1]
	v_cvt_pk_bf16_f32 v74, v82, v83
	v_cvt_pk_bf16_f32 v75, v84, v85
	v_cvt_pk_bf16_f32 v76, v76, v77
	v_cvt_pk_bf16_f32 v77, v90, v91
	flat_store_dwordx4 v[98:99], v[74:77] offset:256 sc1
	v_pk_mul_f32 v[80:81], v[130:131], v[80:81] op_sel_hi:[0,1]
	v_pk_mul_f32 v[78:79], v[130:131], v[78:79] op_sel_hi:[0,1]
	v_add_u32_e32 v74, 48, v131
	v_pk_mul_f32 v[76:77], v[130:131], v[88:89] op_sel_hi:[0,1]
	v_mad_i64_i32 v[82:83], s[0:1], v74, s54, v[132:133]
	v_pk_mul_f32 v[74:75], v[130:131], v[86:87] op_sel_hi:[0,1]
	v_cvt_pk_bf16_f32 v74, v74, v75
	v_cvt_pk_bf16_f32 v75, v76, v77
	v_cvt_pk_bf16_f32 v76, v78, v79
	v_cvt_pk_bf16_f32 v77, v80, v81
	flat_store_dwordx4 v[82:83], v[74:77] sc1
	v_pk_mul_f32 v[72:73], v[130:131], v[72:73] op_sel_hi:[0,1]
	v_pk_mul_f32 v[70:71], v[130:131], v[70:71] op_sel_hi:[0,1]
	v_pk_mul_f32 v[74:75], v[130:131], v[68:69] op_sel_hi:[0,1]
	v_pk_mul_f32 v[68:69], v[130:131], v[66:67] op_sel_hi:[0,1]
	v_cvt_pk_bf16_f32 v66, v70, v71
	v_cvt_pk_bf16_f32 v67, v72, v73
	v_cvt_pk_bf16_f32 v68, v68, v69
	v_cvt_pk_bf16_f32 v69, v74, v75
	flat_store_dwordx4 v[82:83], v[66:69] offset:256 sc1
	v_pk_mul_f32 v[64:65], v[130:131], v[64:65] op_sel_hi:[0,1]
	v_pk_mul_f32 v[62:63], v[130:131], v[62:63] op_sel_hi:[0,1]
	v_add_u32_e32 v66, 0x80, v131
	v_pk_mul_f32 v[68:69], v[130:131], v[60:61] op_sel_hi:[0,1]
	v_pk_mul_f32 v[60:61], v[130:131], v[58:59] op_sel_hi:[0,1]
	v_mad_i64_i32 v[66:67], s[0:1], v66, s54, v[132:133]
	v_cvt_pk_bf16_f32 v58, v62, v63
	v_cvt_pk_bf16_f32 v59, v64, v65
	v_cvt_pk_bf16_f32 v60, v60, v61
	v_cvt_pk_bf16_f32 v61, v68, v69
	flat_store_dwordx4 v[66:67], v[58:61] sc1
	v_pk_mul_f32 v[52:53], v[130:131], v[52:53] op_sel_hi:[0,1]
	v_pk_mul_f32 v[50:51], v[130:131], v[50:51] op_sel_hi:[0,1]
	v_pk_mul_f32 v[58:59], v[130:131], v[44:45] op_sel_hi:[0,1]
	v_pk_mul_f32 v[44:45], v[130:131], v[42:43] op_sel_hi:[0,1]
	v_cvt_pk_bf16_f32 v42, v50, v51
	v_cvt_pk_bf16_f32 v43, v52, v53
	v_cvt_pk_bf16_f32 v44, v44, v45
	v_cvt_pk_bf16_f32 v45, v58, v59
	flat_store_dwordx4 v[66:67], v[42:45] offset:256 sc1
	v_pk_mul_f32 v[48:49], v[130:131], v[48:49] op_sel_hi:[0,1]
	v_pk_mul_f32 v[46:47], v[130:131], v[46:47] op_sel_hi:[0,1]
	v_add_u32_e32 v42, 0x90, v131
	v_pk_mul_f32 v[44:45], v[130:131], v[56:57] op_sel_hi:[0,1]
	v_mad_i64_i32 v[50:51], s[0:1], v42, s54, v[132:133]
	v_pk_mul_f32 v[42:43], v[130:131], v[54:55] op_sel_hi:[0,1]
	v_cvt_pk_bf16_f32 v42, v42, v43
	v_cvt_pk_bf16_f32 v43, v44, v45
	v_cvt_pk_bf16_f32 v44, v46, v47
	v_cvt_pk_bf16_f32 v45, v48, v49
	flat_store_dwordx4 v[50:51], v[42:45] sc1
	v_pk_mul_f32 v[36:37], v[130:131], v[36:37] op_sel_hi:[0,1]
	v_pk_mul_f32 v[34:35], v[130:131], v[34:35] op_sel_hi:[0,1]
	v_pk_mul_f32 v[42:43], v[130:131], v[28:29] op_sel_hi:[0,1]
	v_pk_mul_f32 v[28:29], v[130:131], v[26:27] op_sel_hi:[0,1]
	v_cvt_pk_bf16_f32 v26, v34, v35
	v_cvt_pk_bf16_f32 v27, v36, v37
	v_cvt_pk_bf16_f32 v28, v28, v29
	v_cvt_pk_bf16_f32 v29, v42, v43
	flat_store_dwordx4 v[50:51], v[26:29] offset:256 sc1
	v_pk_mul_f32 v[32:33], v[130:131], v[32:33] op_sel_hi:[0,1]
	v_pk_mul_f32 v[30:31], v[130:131], v[30:31] op_sel_hi:[0,1]
	v_add_u32_e32 v26, 0xa0, v131
	v_pk_mul_f32 v[28:29], v[130:131], v[40:41] op_sel_hi:[0,1]
	v_mad_i64_i32 v[34:35], s[0:1], v26, s54, v[132:133]
	v_pk_mul_f32 v[26:27], v[130:131], v[38:39] op_sel_hi:[0,1]
	v_cvt_pk_bf16_f32 v26, v26, v27
	v_cvt_pk_bf16_f32 v27, v28, v29
	v_cvt_pk_bf16_f32 v28, v30, v31
	v_cvt_pk_bf16_f32 v29, v32, v33
	flat_store_dwordx4 v[34:35], v[26:29] sc1
	v_pk_mul_f32 v[20:21], v[130:131], v[20:21] op_sel_hi:[0,1]
	v_pk_mul_f32 v[18:19], v[130:131], v[18:19] op_sel_hi:[0,1]
	v_pk_mul_f32 v[26:27], v[130:131], v[12:13] op_sel_hi:[0,1]
	v_pk_mul_f32 v[12:13], v[130:131], v[10:11] op_sel_hi:[0,1]
	v_cvt_pk_bf16_f32 v10, v18, v19
	v_cvt_pk_bf16_f32 v11, v20, v21
	v_cvt_pk_bf16_f32 v12, v12, v13
	v_cvt_pk_bf16_f32 v13, v26, v27
	flat_store_dwordx4 v[34:35], v[10:13] offset:256 sc1
	v_pk_mul_f32 v[16:17], v[130:131], v[16:17] op_sel_hi:[0,1]
	v_pk_mul_f32 v[14:15], v[130:131], v[14:15] op_sel_hi:[0,1]
	v_add_u32_e32 v10, 0xb0, v131
	v_pk_mul_f32 v[12:13], v[130:131], v[24:25] op_sel_hi:[0,1]
	v_mad_i64_i32 v[18:19], s[0:1], v10, s54, v[132:133]
	v_pk_mul_f32 v[10:11], v[130:131], v[22:23] op_sel_hi:[0,1]
	v_cvt_pk_bf16_f32 v10, v10, v11
	v_cvt_pk_bf16_f32 v11, v12, v13
	v_cvt_pk_bf16_f32 v12, v14, v15
	v_cvt_pk_bf16_f32 v13, v16, v17
	flat_store_dwordx4 v[18:19], v[10:13] sc1
	v_pk_mul_f32 v[8:9], v[130:131], v[8:9] op_sel_hi:[0,1]
	v_pk_mul_f32 v[6:7], v[130:131], v[6:7] op_sel_hi:[0,1]
	v_pk_mul_f32 v[10:11], v[130:131], v[4:5] op_sel_hi:[0,1]
	v_pk_mul_f32 v[4:5], v[130:131], v[2:3] op_sel_hi:[0,1]
	v_cvt_pk_bf16_f32 v2, v6, v7
	v_cvt_pk_bf16_f32 v3, v8, v9
	v_cvt_pk_bf16_f32 v4, v4, v5
	v_cvt_pk_bf16_f32 v5, v10, v11
	flat_store_dwordx4 v[18:19], v[2:5] offset:256 sc1
	s_branch .LBB0_274

.LBB0_895:
	ds_read_b128 v[156:159], v152
	ds_read_b128 v[160:163], v152 offset:1024
	ds_read_b128 v[164:167], v152 offset:2048
	ds_read_b128 v[168:171], v152 offset:3072
	s_add_u32 s0, s30, 0xfffc0080
	s_addc_u32 s1, s31, -1
	s_cmp_eq_u32 s55, 12
	s_cselect_b32 s37, s23, s1
	s_cselect_b32 s36, s51, s0
	s_cselect_b32 s35, s21, s54
	s_cselect_b32 s34, s52, s53
	v_lshl_add_u64 v[148:149], s[30:31], 0, v[140:141]
	s_add_i32 m0, s25, 0xc000
	ds_read_b128 v[172:175], v153
	ds_read_b128 v[176:179], v153 offset:1024
	ds_read_b128 v[180:183], v153 offset:2048
	ds_read_b128 v[184:187], v153 offset:3072
	ds_read_b128 v[188:191], v153 offset:4096
	ds_read_b128 v[192:195], v153 offset:5120
	ds_read_b128 v[196:199], v153 offset:6144
	ds_read_b128 v[200:203], v153 offset:7168
	global_load_lds_dwordx4 v[148:149], off
	v_lshl_add_u64 v[148:149], s[30:31], 0, v[138:139]
	s_add_i32 m0, s25, 0xe000
	s_nop 0
	global_load_lds_dwordx4 v[148:149], off
	s_waitcnt lgkmcnt(8)
	s_waitcnt vmcnt(10)
	s_barrier
	s_waitcnt lgkmcnt(0)
	s_setprio 1
	s_waitcnt lgkmcnt(0)
	v_mfma_f32_16x16x32_bf16 v[126:129], v[156:159], v[172:175], v[126:129]
	v_mfma_f32_16x16x32_bf16 v[122:125], v[164:167], v[172:175], v[122:125]
	v_mfma_f32_16x16x32_bf16 v[118:121], v[156:159], v[180:183], v[118:121]
	v_mfma_f32_16x16x32_bf16 v[110:113], v[164:167], v[180:183], v[110:113]
	v_mfma_f32_16x16x32_bf16 v[102:105], v[156:159], v[188:191], v[102:105]
	v_mfma_f32_16x16x32_bf16 v[94:97], v[164:167], v[188:191], v[94:97]
	v_mfma_f32_16x16x32_bf16 v[86:89], v[156:159], v[196:199], v[86:89]
	v_mfma_f32_16x16x32_bf16 v[78:81], v[164:167], v[196:199], v[78:81]
	v_mfma_f32_16x16x32_bf16 v[126:129], v[160:163], v[176:179], v[126:129]
	v_mfma_f32_16x16x32_bf16 v[122:125], v[168:171], v[176:179], v[122:125]
	v_mfma_f32_16x16x32_bf16 v[118:121], v[160:163], v[184:187], v[118:121]
	v_mfma_f32_16x16x32_bf16 v[110:113], v[168:171], v[184:187], v[110:113]
	v_mfma_f32_16x16x32_bf16 v[102:105], v[160:163], v[192:195], v[102:105]
	v_mfma_f32_16x16x32_bf16 v[94:97], v[168:171], v[192:195], v[94:97]
	v_mfma_f32_16x16x32_bf16 v[86:89], v[160:163], v[200:203], v[86:89]
	v_mfma_f32_16x16x32_bf16 v[78:81], v[168:171], v[200:203], v[78:81]
	s_setprio 0
	s_barrier
	s_add_i32 s0, s47, s11
	v_lshl_add_u64 v[148:149], s[34:35], 0, v[134:135]
	s_mov_b32 m0, s0
	ds_read_b128 v[204:207], v154
	ds_read_b128 v[208:211], v154 offset:1024
	ds_read_b128 v[212:215], v154 offset:2048
	ds_read_b128 v[216:219], v154 offset:3072
	global_load_lds_dwordx4 v[148:149], off
	v_lshl_add_u64 v[220:221], s[34:35], 0, v[130:131]
	s_add_i32 m0, s0, 0x2000
	s_nop 0
	global_load_lds_dwordx4 v[220:221], off
	s_waitcnt vmcnt(10)
	s_barrier
	s_waitcnt lgkmcnt(0)
	s_setprio 1
	s_waitcnt lgkmcnt(0)
	v_mfma_f32_16x16x32_bf16 v[114:117], v[204:207], v[172:175], v[114:117]
	v_mfma_f32_16x16x32_bf16 v[106:109], v[212:215], v[172:175], v[106:109]
	v_mfma_f32_16x16x32_bf16 v[98:101], v[204:207], v[180:183], v[98:101]
	v_mfma_f32_16x16x32_bf16 v[90:93], v[212:215], v[180:183], v[90:93]
	v_mfma_f32_16x16x32_bf16 v[82:85], v[204:207], v[188:191], v[82:85]
	v_mfma_f32_16x16x32_bf16 v[74:77], v[212:215], v[188:191], v[74:77]
	v_mfma_f32_16x16x32_bf16 v[70:73], v[204:207], v[196:199], v[70:73]
	v_mfma_f32_16x16x32_bf16 v[66:69], v[212:215], v[196:199], v[66:69]
	v_mfma_f32_16x16x32_bf16 v[114:117], v[208:211], v[176:179], v[114:117]
	v_mfma_f32_16x16x32_bf16 v[106:109], v[216:219], v[176:179], v[106:109]
	v_mfma_f32_16x16x32_bf16 v[98:101], v[208:211], v[184:187], v[98:101]
	v_mfma_f32_16x16x32_bf16 v[90:93], v[216:219], v[184:187], v[90:93]
	v_mfma_f32_16x16x32_bf16 v[82:85], v[208:211], v[192:195], v[82:85]
	v_mfma_f32_16x16x32_bf16 v[74:77], v[216:219], v[192:195], v[74:77]
	v_mfma_f32_16x16x32_bf16 v[70:73], v[208:211], v[200:203], v[70:73]
	v_mfma_f32_16x16x32_bf16 v[66:69], v[216:219], v[200:203], v[66:69]
	s_setprio 0
	s_mov_b32 m0, s25
	v_lshl_add_u64 v[222:223], s[36:37], 0, v[136:137]
	s_barrier
	ds_read_b128 v[172:175], v153 offset:16384
	ds_read_b128 v[176:179], v153 offset:17408
	ds_read_b128 v[180:183], v153 offset:18432
	ds_read_b128 v[184:187], v153 offset:19456
	ds_read_b128 v[188:191], v153 offset:20480
	ds_read_b128 v[192:195], v153 offset:21504
	ds_read_b128 v[196:199], v153 offset:22528
	ds_read_b128 v[200:203], v153 offset:23552
	global_load_lds_dwordx4 v[222:223], off
	v_lshl_add_u64 v[224:225], s[36:37], 0, v[132:133]
	s_mov_b32 m0, s39
	s_nop 0
	global_load_lds_dwordx4 v[224:225], off
	s_waitcnt vmcnt(10)
	s_barrier
	s_waitcnt lgkmcnt(0)
	s_setprio 1
	s_waitcnt lgkmcnt(0)
	v_mfma_f32_16x16x32_bf16 v[62:65], v[156:159], v[172:175], v[62:65]
	v_mfma_f32_16x16x32_bf16 v[58:61], v[164:167], v[172:175], v[58:61]
	v_mfma_f32_16x16x32_bf16 v[54:57], v[156:159], v[180:183], v[54:57]
	v_mfma_f32_16x16x32_bf16 v[46:49], v[164:167], v[180:183], v[46:49]
	v_mfma_f32_16x16x32_bf16 v[38:41], v[156:159], v[188:191], v[38:41]
	v_mfma_f32_16x16x32_bf16 v[30:33], v[164:167], v[188:191], v[30:33]
	v_mfma_f32_16x16x32_bf16 v[22:25], v[156:159], v[196:199], v[22:25]
	v_mfma_f32_16x16x32_bf16 v[14:17], v[164:167], v[196:199], v[14:17]
	v_mfma_f32_16x16x32_bf16 v[62:65], v[160:163], v[176:179], v[62:65]
	v_mfma_f32_16x16x32_bf16 v[58:61], v[168:171], v[176:179], v[58:61]
	v_mfma_f32_16x16x32_bf16 v[54:57], v[160:163], v[184:187], v[54:57]
	v_mfma_f32_16x16x32_bf16 v[46:49], v[168:171], v[184:187], v[46:49]
	v_mfma_f32_16x16x32_bf16 v[38:41], v[160:163], v[192:195], v[38:41]
	v_mfma_f32_16x16x32_bf16 v[30:33], v[168:171], v[192:195], v[30:33]
	v_mfma_f32_16x16x32_bf16 v[22:25], v[160:163], v[200:203], v[22:25]
	v_mfma_f32_16x16x32_bf16 v[14:17], v[168:171], v[200:203], v[14:17]
	s_setprio 0
	s_barrier
	s_add_u32 s0, s34, 0x40000
	s_addc_u32 s1, s35, 0
	s_add_i32 s56, s48, s11
	v_lshl_add_u64 v[156:157], s[0:1], 0, v[134:135]
	s_mov_b32 m0, s56
	s_nop 0
	global_load_lds_dwordx4 v[156:157], off
	v_lshl_add_u64 v[156:157], s[0:1], 0, v[130:131]
	s_add_i32 m0, s56, 0x2000
	s_nop 0
	global_load_lds_dwordx4 v[156:157], off
	s_waitcnt vmcnt(10)
	s_barrier
	s_setprio 1
	v_mfma_f32_16x16x32_bf16 v[50:53], v[204:207], v[172:175], v[50:53]
	v_mfma_f32_16x16x32_bf16 v[42:45], v[212:215], v[172:175], v[42:45]
	v_mfma_f32_16x16x32_bf16 v[34:37], v[204:207], v[180:183], v[34:37]
	v_mfma_f32_16x16x32_bf16 v[26:29], v[212:215], v[180:183], v[26:29]
	v_mfma_f32_16x16x32_bf16 v[18:21], v[204:207], v[188:191], v[18:21]
	v_mfma_f32_16x16x32_bf16 v[10:13], v[212:215], v[188:191], v[10:13]
	v_mfma_f32_16x16x32_bf16 v[6:9], v[204:207], v[196:199], v[6:9]
	v_mfma_f32_16x16x32_bf16 v[2:5], v[212:215], v[196:199], v[2:5]
	v_mfma_f32_16x16x32_bf16 v[50:53], v[208:211], v[176:179], v[50:53]
	v_mfma_f32_16x16x32_bf16 v[42:45], v[216:219], v[176:179], v[42:45]
	v_mfma_f32_16x16x32_bf16 v[34:37], v[208:211], v[184:187], v[34:37]
	v_mfma_f32_16x16x32_bf16 v[26:29], v[216:219], v[184:187], v[26:29]
	v_mfma_f32_16x16x32_bf16 v[18:21], v[208:211], v[192:195], v[18:21]
	v_mfma_f32_16x16x32_bf16 v[10:13], v[216:219], v[192:195], v[10:13]
	v_mfma_f32_16x16x32_bf16 v[6:9], v[208:211], v[200:203], v[6:9]
	v_mfma_f32_16x16x32_bf16 v[2:5], v[216:219], v[200:203], v[2:5]
	s_setprio 0
	s_add_i32 s56, 0, 0x18000
	v_add_u32_e32 v146, s56, v151
	s_barrier
	ds_read_b128 v[156:159], v146
	ds_read_b128 v[160:163], v146 offset:1024
	ds_read_b128 v[164:167], v146 offset:2048
	ds_read_b128 v[168:171], v146 offset:3072
	s_add_u32 s0, s36, 0x40000
	s_addc_u32 s1, s37, 0
	s_mov_b32 m0, s40
	v_lshl_add_u64 v[204:205], s[0:1], 0, v[136:137]
	ds_read_b128 v[172:175], v153 offset:32768
	ds_read_b128 v[176:179], v153 offset:33792
	ds_read_b128 v[180:183], v153 offset:34816
	ds_read_b128 v[184:187], v153 offset:35840
	ds_read_b128 v[188:191], v153 offset:36864
	ds_read_b128 v[192:195], v153 offset:37888
	ds_read_b128 v[196:199], v153 offset:38912
	ds_read_b128 v[200:203], v153 offset:39936
	global_load_lds_dwordx4 v[204:205], off
	v_lshl_add_u64 v[204:205], s[0:1], 0, v[132:133]
	s_mov_b32 m0, s41
	s_nop 0
	global_load_lds_dwordx4 v[204:205], off
	s_waitcnt lgkmcnt(8)
	s_waitcnt vmcnt(10)
	s_barrier
	s_waitcnt lgkmcnt(0)
	s_setprio 1
	s_waitcnt lgkmcnt(0)
	v_mfma_f32_16x16x32_bf16 v[126:129], v[156:159], v[172:175], v[126:129]
	v_mfma_f32_16x16x32_bf16 v[122:125], v[164:167], v[172:175], v[122:125]
	v_mfma_f32_16x16x32_bf16 v[118:121], v[156:159], v[180:183], v[118:121]
	v_mfma_f32_16x16x32_bf16 v[110:113], v[164:167], v[180:183], v[110:113]
	v_mfma_f32_16x16x32_bf16 v[102:105], v[156:159], v[188:191], v[102:105]
	v_mfma_f32_16x16x32_bf16 v[94:97], v[164:167], v[188:191], v[94:97]
	v_mfma_f32_16x16x32_bf16 v[86:89], v[156:159], v[196:199], v[86:89]
	v_mfma_f32_16x16x32_bf16 v[78:81], v[164:167], v[196:199], v[78:81]
	v_mfma_f32_16x16x32_bf16 v[126:129], v[160:163], v[176:179], v[126:129]
	v_mfma_f32_16x16x32_bf16 v[122:125], v[168:171], v[176:179], v[122:125]
	v_mfma_f32_16x16x32_bf16 v[118:121], v[160:163], v[184:187], v[118:121]
	v_mfma_f32_16x16x32_bf16 v[110:113], v[168:171], v[184:187], v[110:113]
	v_mfma_f32_16x16x32_bf16 v[102:105], v[160:163], v[192:195], v[102:105]
	v_mfma_f32_16x16x32_bf16 v[94:97], v[168:171], v[192:195], v[94:97]
	v_mfma_f32_16x16x32_bf16 v[86:89], v[160:163], v[200:203], v[86:89]
	v_mfma_f32_16x16x32_bf16 v[78:81], v[168:171], v[200:203], v[78:81]
	s_setprio 0
	s_barrier
	s_add_i32 s36, 0, 0x1c000
	s_add_i32 s0, s56, s11
	v_add_u32_e32 v146, s36, v151
	v_lshl_add_u64 v[148:149], v[148:149], 0, s[16:17]
	s_mov_b32 m0, s0
	ds_read_b128 v[204:207], v146
	ds_read_b128 v[208:211], v146 offset:1024
	ds_read_b128 v[212:215], v146 offset:2048
	ds_read_b128 v[216:219], v146 offset:3072
	global_load_lds_dwordx4 v[148:149], off
	v_lshl_add_u64 v[148:149], v[220:221], 0, s[16:17]
	s_add_i32 m0, s0, 0x2000
	s_nop 0
	global_load_lds_dwordx4 v[148:149], off
	s_waitcnt vmcnt(10)
	s_barrier
	s_waitcnt lgkmcnt(0)
	s_setprio 1
	s_waitcnt lgkmcnt(0)
	v_mfma_f32_16x16x32_bf16 v[114:117], v[204:207], v[172:175], v[114:117]
	v_mfma_f32_16x16x32_bf16 v[106:109], v[212:215], v[172:175], v[106:109]
	v_mfma_f32_16x16x32_bf16 v[98:101], v[204:207], v[180:183], v[98:101]
	v_mfma_f32_16x16x32_bf16 v[90:93], v[212:215], v[180:183], v[90:93]
	v_mfma_f32_16x16x32_bf16 v[82:85], v[204:207], v[188:191], v[82:85]
	v_mfma_f32_16x16x32_bf16 v[74:77], v[212:215], v[188:191], v[74:77]
	v_mfma_f32_16x16x32_bf16 v[70:73], v[204:207], v[196:199], v[70:73]
	v_mfma_f32_16x16x32_bf16 v[66:69], v[212:215], v[196:199], v[66:69]
	v_mfma_f32_16x16x32_bf16 v[114:117], v[208:211], v[176:179], v[114:117]
	v_mfma_f32_16x16x32_bf16 v[106:109], v[216:219], v[176:179], v[106:109]
	v_mfma_f32_16x16x32_bf16 v[98:101], v[208:211], v[184:187], v[98:101]
	v_mfma_f32_16x16x32_bf16 v[90:93], v[216:219], v[184:187], v[90:93]
	v_mfma_f32_16x16x32_bf16 v[82:85], v[208:211], v[192:195], v[82:85]
	v_mfma_f32_16x16x32_bf16 v[74:77], v[216:219], v[192:195], v[74:77]
	v_mfma_f32_16x16x32_bf16 v[70:73], v[208:211], v[200:203], v[70:73]
	v_mfma_f32_16x16x32_bf16 v[66:69], v[216:219], v[200:203], v[66:69]
	s_setprio 0
	s_mov_b32 m0, s45
	v_lshl_add_u64 v[148:149], v[222:223], 0, s[16:17]
	s_barrier
	ds_read_b128 v[172:175], v153 offset:49152
	ds_read_b128 v[176:179], v153 offset:50176
	ds_read_b128 v[180:183], v153 offset:51200
	ds_read_b128 v[184:187], v153 offset:52224
	ds_read_b128 v[188:191], v153 offset:53248
	ds_read_b128 v[192:195], v153 offset:54272
	ds_read_b128 v[196:199], v153 offset:55296
	ds_read_b128 v[200:203], v153 offset:56320
	global_load_lds_dwordx4 v[148:149], off
	v_lshl_add_u64 v[148:149], v[224:225], 0, s[16:17]
	s_mov_b32 m0, s46
	s_nop 0
	global_load_lds_dwordx4 v[148:149], off
	s_waitcnt vmcnt(10)
	s_barrier
	s_waitcnt lgkmcnt(0)
	s_setprio 1
	s_waitcnt lgkmcnt(0)
	v_mfma_f32_16x16x32_bf16 v[62:65], v[156:159], v[172:175], v[62:65]
	v_mfma_f32_16x16x32_bf16 v[58:61], v[164:167], v[172:175], v[58:61]
	v_mfma_f32_16x16x32_bf16 v[54:57], v[156:159], v[180:183], v[54:57]
	v_mfma_f32_16x16x32_bf16 v[46:49], v[164:167], v[180:183], v[46:49]
	v_mfma_f32_16x16x32_bf16 v[38:41], v[156:159], v[188:191], v[38:41]
	v_mfma_f32_16x16x32_bf16 v[30:33], v[164:167], v[188:191], v[30:33]
	v_mfma_f32_16x16x32_bf16 v[22:25], v[156:159], v[196:199], v[22:25]
	v_mfma_f32_16x16x32_bf16 v[14:17], v[164:167], v[196:199], v[14:17]
	v_mfma_f32_16x16x32_bf16 v[62:65], v[160:163], v[176:179], v[62:65]
	v_mfma_f32_16x16x32_bf16 v[58:61], v[168:171], v[176:179], v[58:61]
	v_mfma_f32_16x16x32_bf16 v[54:57], v[160:163], v[184:187], v[54:57]
	v_mfma_f32_16x16x32_bf16 v[46:49], v[168:171], v[184:187], v[46:49]
	v_mfma_f32_16x16x32_bf16 v[38:41], v[160:163], v[192:195], v[38:41]
	v_mfma_f32_16x16x32_bf16 v[30:33], v[168:171], v[192:195], v[30:33]
	v_mfma_f32_16x16x32_bf16 v[22:25], v[160:163], v[200:203], v[22:25]
	v_mfma_f32_16x16x32_bf16 v[14:17], v[168:171], v[200:203], v[14:17]
	s_setprio 0
	s_barrier
	s_add_u32 s0, s34, 0x40080
	s_addc_u32 s1, s35, 0
	s_add_i32 s34, s36, s11
	v_lshl_add_u64 v[148:149], s[0:1], 0, v[134:135]
	s_mov_b32 m0, s34
	s_nop 0
	global_load_lds_dwordx4 v[148:149], off
	v_lshl_add_u64 v[148:149], s[0:1], 0, v[130:131]
	s_add_i32 m0, s34, 0x2000
	s_nop 0
	global_load_lds_dwordx4 v[148:149], off
	s_waitcnt vmcnt(10)
	s_barrier
	s_setprio 1
	v_mfma_f32_16x16x32_bf16 v[50:53], v[204:207], v[172:175], v[50:53]
	v_mfma_f32_16x16x32_bf16 v[42:45], v[212:215], v[172:175], v[42:45]
	v_mfma_f32_16x16x32_bf16 v[34:37], v[204:207], v[180:183], v[34:37]
	v_mfma_f32_16x16x32_bf16 v[26:29], v[212:215], v[180:183], v[26:29]
	v_mfma_f32_16x16x32_bf16 v[18:21], v[204:207], v[188:191], v[18:21]
	v_mfma_f32_16x16x32_bf16 v[10:13], v[212:215], v[188:191], v[10:13]
	v_mfma_f32_16x16x32_bf16 v[6:9], v[204:207], v[196:199], v[6:9]
	v_mfma_f32_16x16x32_bf16 v[2:5], v[212:215], v[196:199], v[2:5]
	v_mfma_f32_16x16x32_bf16 v[50:53], v[208:211], v[176:179], v[50:53]
	v_mfma_f32_16x16x32_bf16 v[42:45], v[216:219], v[176:179], v[42:45]
	v_mfma_f32_16x16x32_bf16 v[34:37], v[208:211], v[184:187], v[34:37]
	v_mfma_f32_16x16x32_bf16 v[26:29], v[216:219], v[184:187], v[26:29]
	v_mfma_f32_16x16x32_bf16 v[18:21], v[208:211], v[192:195], v[18:21]
	v_mfma_f32_16x16x32_bf16 v[10:13], v[216:219], v[192:195], v[10:13]
	v_mfma_f32_16x16x32_bf16 v[6:9], v[208:211], v[200:203], v[6:9]
	v_mfma_f32_16x16x32_bf16 v[2:5], v[216:219], v[200:203], v[2:5]
	s_setprio 0
	s_add_i32 s55, s55, 2
	s_add_u32 s53, s53, 0x100
	s_addc_u32 s54, s54, 0
	s_add_u32 s30, s30, 0x100
	s_addc_u32 s31, s31, 0
	s_cmp_gt_u32 s55, 13
	s_barrier
	s_cbranch_scc0 .LBB0_895
	v_mov_b32_e32 v156, v147
	v_mov_b32_e32 v146, v150
	s_cmp_gt_i32 s50, 11
	s_mov_b64 s[30:31], -1
	s_cbranch_scc0 .LBB0_900
	s_cmp_eq_u32 s50, 12
	s_cselect_b64 s[0:1], -1, 0
	s_and_b64 s[0:1], s[0:1], s[18:19]
	v_cmp_gt_i32_e32 vcc, 4, v146
	s_and_b64 s[0:1], s[0:1], vcc
	s_and_saveexec_b64 s[30:31], s[0:1]
	s_cbranch_execz .LBB0_899
	s_lshl_b32 s0, s24, 8
	s_add_i32 s0, s0, s43
	v_add_u32_e32 v157, s0, v156
	v_mov_b32_e32 v158, v157
	v_lshlrev_b32_e32 v148, 3, v146
	v_ashrrev_i32_e32 v149, 31, v148
	v_ashrrev_i32_e32 v159, 31, v158
	v_lshlrev_b64 v[158:159], 7, v[158:159]
	v_lshl_add_u64 v[158:159], s[14:15], 0, v[158:159]
	v_lshlrev_b64 v[148:149], 2, v[148:149]
	v_lshl_add_u64 v[162:163], v[158:159], 0, v[148:149]
	v_pk_add_f32 v[160:161], v[128:129], 0 op_sel_hi:[1,0]
	v_pk_add_f32 v[158:159], v[126:127], 0 op_sel_hi:[1,0]
	flat_store_dwordx4 v[162:163], v[158:161] sc1
	s_nop 1
	v_pk_add_f32 v[160:161], v[124:125], 0 op_sel_hi:[1,0]
	v_pk_add_f32 v[158:159], v[122:123], 0 op_sel_hi:[1,0]
	flat_store_dwordx4 v[162:163], v[158:161] offset:16 sc1
	s_nop 1
	v_add_u32_e32 v158, 16, v157
	v_pk_add_f32 v[160:161], v[120:121], 0 op_sel_hi:[1,0]
	v_ashrrev_i32_e32 v159, 31, v158
	v_lshlrev_b64 v[158:159], 7, v[158:159]
	v_lshl_add_u64 v[158:159], s[14:15], 0, v[158:159]
	v_lshl_add_u64 v[162:163], v[158:159], 0, v[148:149]
	v_pk_add_f32 v[158:159], v[118:119], 0 op_sel_hi:[1,0]
	flat_store_dwordx4 v[162:163], v[158:161] sc1
	s_nop 1
	v_pk_add_f32 v[160:161], v[112:113], 0 op_sel_hi:[1,0]
	v_pk_add_f32 v[158:159], v[110:111], 0 op_sel_hi:[1,0]
	flat_store_dwordx4 v[162:163], v[158:161] offset:16 sc1
	s_nop 1
	v_add_u32_e32 v158, 32, v157
	v_pk_add_f32 v[160:161], v[104:105], 0 op_sel_hi:[1,0]
	v_ashrrev_i32_e32 v159, 31, v158
	v_lshlrev_b64 v[158:159], 7, v[158:159]
	v_lshl_add_u64 v[158:159], s[14:15], 0, v[158:159]
	v_lshl_add_u64 v[162:163], v[158:159], 0, v[148:149]
	v_pk_add_f32 v[158:159], v[102:103], 0 op_sel_hi:[1,0]
	flat_store_dwordx4 v[162:163], v[158:161] sc1
	s_nop 1
	v_pk_add_f32 v[160:161], v[96:97], 0 op_sel_hi:[1,0]
	v_pk_add_f32 v[158:159], v[94:95], 0 op_sel_hi:[1,0]
	flat_store_dwordx4 v[162:163], v[158:161] offset:16 sc1
	s_nop 1
	v_add_u32_e32 v158, 48, v157
	v_pk_add_f32 v[160:161], v[88:89], 0 op_sel_hi:[1,0]
	v_ashrrev_i32_e32 v159, 31, v158
	v_lshlrev_b64 v[158:159], 7, v[158:159]
	v_lshl_add_u64 v[158:159], s[14:15], 0, v[158:159]
	v_lshl_add_u64 v[162:163], v[158:159], 0, v[148:149]
	v_pk_add_f32 v[158:159], v[86:87], 0 op_sel_hi:[1,0]
	flat_store_dwordx4 v[162:163], v[158:161] sc1
	s_nop 1
	v_pk_add_f32 v[160:161], v[80:81], 0 op_sel_hi:[1,0]
	v_pk_add_f32 v[158:159], v[78:79], 0 op_sel_hi:[1,0]
	flat_store_dwordx4 v[162:163], v[158:161] offset:16 sc1
	s_nop 1
	v_add_u32_e32 v158, 0x80, v157
	v_pk_add_f32 v[160:161], v[64:65], 0 op_sel_hi:[1,0]
	v_ashrrev_i32_e32 v159, 31, v158
	v_lshlrev_b64 v[158:159], 7, v[158:159]
	v_lshl_add_u64 v[158:159], s[14:15], 0, v[158:159]
	v_lshl_add_u64 v[162:163], v[158:159], 0, v[148:149]
	v_pk_add_f32 v[158:159], v[62:63], 0 op_sel_hi:[1,0]
	flat_store_dwordx4 v[162:163], v[158:161] sc1
	s_nop 1
	v_pk_add_f32 v[160:161], v[60:61], 0 op_sel_hi:[1,0]
	v_pk_add_f32 v[158:159], v[58:59], 0 op_sel_hi:[1,0]
	flat_store_dwordx4 v[162:163], v[158:161] offset:16 sc1
	s_nop 1
	v_add_u32_e32 v158, 0x90, v157
	v_pk_add_f32 v[160:161], v[56:57], 0 op_sel_hi:[1,0]
	v_ashrrev_i32_e32 v159, 31, v158
	v_lshlrev_b64 v[158:159], 7, v[158:159]
	v_lshl_add_u64 v[158:159], s[14:15], 0, v[158:159]
	v_lshl_add_u64 v[162:163], v[158:159], 0, v[148:149]
	v_pk_add_f32 v[158:159], v[54:55], 0 op_sel_hi:[1,0]
	flat_store_dwordx4 v[162:163], v[158:161] sc1
	s_nop 1
	v_pk_add_f32 v[160:161], v[48:49], 0 op_sel_hi:[1,0]
	v_pk_add_f32 v[158:159], v[46:47], 0 op_sel_hi:[1,0]
	flat_store_dwordx4 v[162:163], v[158:161] offset:16 sc1
	s_nop 1
	v_add_u32_e32 v158, 0xa0, v157
	v_pk_add_f32 v[160:161], v[40:41], 0 op_sel_hi:[1,0]
	v_ashrrev_i32_e32 v159, 31, v158
	v_lshlrev_b64 v[158:159], 7, v[158:159]
	v_lshl_add_u64 v[158:159], s[14:15], 0, v[158:159]
	v_lshl_add_u64 v[162:163], v[158:159], 0, v[148:149]
	v_pk_add_f32 v[158:159], v[38:39], 0 op_sel_hi:[1,0]
	flat_store_dwordx4 v[162:163], v[158:161] sc1
	s_nop 1
	v_pk_add_f32 v[160:161], v[32:33], 0 op_sel_hi:[1,0]
	v_pk_add_f32 v[158:159], v[30:31], 0 op_sel_hi:[1,0]
	flat_store_dwordx4 v[162:163], v[158:161] offset:16 sc1
	s_nop 1
	v_add_u32_e32 v158, 0xb0, v157
	v_pk_add_f32 v[160:161], v[24:25], 0 op_sel_hi:[1,0]
	v_ashrrev_i32_e32 v159, 31, v158
	v_lshlrev_b64 v[158:159], 7, v[158:159]
	v_lshl_add_u64 v[158:159], s[14:15], 0, v[158:159]
	v_lshl_add_u64 v[148:149], v[158:159], 0, v[148:149]
	v_pk_add_f32 v[158:159], v[22:23], 0 op_sel_hi:[1,0]
	flat_store_dwordx4 v[148:149], v[158:161] sc1
	s_nop 1
	v_pk_add_f32 v[160:161], v[16:17], 0 op_sel_hi:[1,0]
	v_pk_add_f32 v[158:159], v[14:15], 0 op_sel_hi:[1,0]
	flat_store_dwordx4 v[148:149], v[158:161] offset:16 sc1

.LBB0_900:
	s_andn2_b64 vcc, exec, s[30:31]
	s_cbranch_vccnz .LBB0_891
	s_lshl_b32 s0, s50, 8
	s_or_b32 s0, s0, s44
	s_cmp_lt_i32 s50, 2
	v_lshl_add_u32 v148, v146, 3, s0
	s_cselect_b64 vcc, -1, 0
	s_lshl_b32 s0, s24, 8
	s_add_i32 s0, s0, s43
	v_add_u32_e32 v160, s0, v156
	v_cndmask_b32_e32 v146, 1.0, v155, vcc
	v_ashrrev_i32_e32 v149, 31, v148
	v_mov_b32_e32 v156, v160
	v_lshl_add_u64 v[148:149], v[148:149], 1, s[12:13]
	v_pk_mul_f32 v[128:129], v[146:147], v[128:129] op_sel_hi:[0,1]
	v_pk_mul_f32 v[126:127], v[146:147], v[126:127] op_sel_hi:[0,1]
	v_pk_mul_f32 v[158:159], v[146:147], v[124:125] op_sel_hi:[0,1]
	v_pk_mul_f32 v[124:125], v[146:147], v[122:123] op_sel_hi:[0,1]
	v_mad_i64_i32 v[156:157], s[0:1], v156, s49, v[148:149]
	v_cvt_pk_bf16_f32 v122, v126, v127
	v_cvt_pk_bf16_f32 v123, v128, v129
	v_cvt_pk_bf16_f32 v124, v124, v125
	v_cvt_pk_bf16_f32 v125, v158, v159
	flat_store_dwordx4 v[156:157], v[122:125] sc1
	v_pk_mul_f32 v[116:117], v[146:147], v[116:117] op_sel_hi:[0,1]
	v_pk_mul_f32 v[114:115], v[146:147], v[114:115] op_sel_hi:[0,1]
	v_pk_mul_f32 v[122:123], v[146:147], v[108:109] op_sel_hi:[0,1]
	v_pk_mul_f32 v[108:109], v[146:147], v[106:107] op_sel_hi:[0,1]
	v_cvt_pk_bf16_f32 v106, v114, v115
	v_cvt_pk_bf16_f32 v107, v116, v117
	v_cvt_pk_bf16_f32 v108, v108, v109
	v_cvt_pk_bf16_f32 v109, v122, v123
	flat_store_dwordx4 v[156:157], v[106:109] offset:256 sc1
	v_pk_mul_f32 v[112:113], v[146:147], v[112:113] op_sel_hi:[0,1]
	v_pk_mul_f32 v[110:111], v[146:147], v[110:111] op_sel_hi:[0,1]
	v_add_u32_e32 v106, 16, v160
	v_pk_mul_f32 v[108:109], v[146:147], v[120:121] op_sel_hi:[0,1]
	v_mad_i64_i32 v[114:115], s[0:1], v106, s49, v[148:149]
	v_pk_mul_f32 v[106:107], v[146:147], v[118:119] op_sel_hi:[0,1]
	v_cvt_pk_bf16_f32 v106, v106, v107
	v_cvt_pk_bf16_f32 v107, v108, v109
	v_cvt_pk_bf16_f32 v108, v110, v111
	v_cvt_pk_bf16_f32 v109, v112, v113
	flat_store_dwordx4 v[114:115], v[106:109] sc1
	v_pk_mul_f32 v[100:101], v[146:147], v[100:101] op_sel_hi:[0,1]
	v_pk_mul_f32 v[98:99], v[146:147], v[98:99] op_sel_hi:[0,1]
	v_pk_mul_f32 v[106:107], v[146:147], v[92:93] op_sel_hi:[0,1]
	v_pk_mul_f32 v[92:93], v[146:147], v[90:91] op_sel_hi:[0,1]
	v_cvt_pk_bf16_f32 v90, v98, v99
	v_cvt_pk_bf16_f32 v91, v100, v101
	v_cvt_pk_bf16_f32 v92, v92, v93
	v_cvt_pk_bf16_f32 v93, v106, v107
	flat_store_dwordx4 v[114:115], v[90:93] offset:256 sc1
	v_pk_mul_f32 v[96:97], v[146:147], v[96:97] op_sel_hi:[0,1]
	v_pk_mul_f32 v[94:95], v[146:147], v[94:95] op_sel_hi:[0,1]
	v_add_u32_e32 v90, 32, v160
	v_pk_mul_f32 v[92:93], v[146:147], v[104:105] op_sel_hi:[0,1]
	v_mad_i64_i32 v[98:99], s[0:1], v90, s49, v[148:149]
	v_pk_mul_f32 v[90:91], v[146:147], v[102:103] op_sel_hi:[0,1]
	v_cvt_pk_bf16_f32 v90, v90, v91
	v_cvt_pk_bf16_f32 v91, v92, v93
	v_cvt_pk_bf16_f32 v92, v94, v95
	v_cvt_pk_bf16_f32 v93, v96, v97
	flat_store_dwordx4 v[98:99], v[90:93] sc1
	v_pk_mul_f32 v[84:85], v[146:147], v[84:85] op_sel_hi:[0,1]
	v_pk_mul_f32 v[82:83], v[146:147], v[82:83] op_sel_hi:[0,1]
	v_pk_mul_f32 v[90:91], v[146:147], v[76:77] op_sel_hi:[0,1]
	v_pk_mul_f32 v[76:77], v[146:147], v[74:75] op_sel_hi:[0,1]
	v_cvt_pk_bf16_f32 v74, v82, v83
	v_cvt_pk_bf16_f32 v75, v84, v85
	v_cvt_pk_bf16_f32 v76, v76, v77
	v_cvt_pk_bf16_f32 v77, v90, v91
	flat_store_dwordx4 v[98:99], v[74:77] offset:256 sc1
	v_pk_mul_f32 v[80:81], v[146:147], v[80:81] op_sel_hi:[0,1]
	v_pk_mul_f32 v[78:79], v[146:147], v[78:79] op_sel_hi:[0,1]
	v_add_u32_e32 v74, 48, v160
	v_pk_mul_f32 v[76:77], v[146:147], v[88:89] op_sel_hi:[0,1]
	v_mad_i64_i32 v[82:83], s[0:1], v74, s49, v[148:149]
	v_pk_mul_f32 v[74:75], v[146:147], v[86:87] op_sel_hi:[0,1]
	v_cvt_pk_bf16_f32 v74, v74, v75
	v_cvt_pk_bf16_f32 v75, v76, v77
	v_cvt_pk_bf16_f32 v76, v78, v79
	v_cvt_pk_bf16_f32 v77, v80, v81
	flat_store_dwordx4 v[82:83], v[74:77] sc1
	v_pk_mul_f32 v[72:73], v[146:147], v[72:73] op_sel_hi:[0,1]
	v_pk_mul_f32 v[70:71], v[146:147], v[70:71] op_sel_hi:[0,1]
	v_pk_mul_f32 v[74:75], v[146:147], v[68:69] op_sel_hi:[0,1]
	v_pk_mul_f32 v[68:69], v[146:147], v[66:67] op_sel_hi:[0,1]
	v_cvt_pk_bf16_f32 v66, v70, v71
	v_cvt_pk_bf16_f32 v67, v72, v73
	v_cvt_pk_bf16_f32 v68, v68, v69
	v_cvt_pk_bf16_f32 v69, v74, v75
	flat_store_dwordx4 v[82:83], v[66:69] offset:256 sc1
	v_pk_mul_f32 v[64:65], v[146:147], v[64:65] op_sel_hi:[0,1]
	v_pk_mul_f32 v[62:63], v[146:147], v[62:63] op_sel_hi:[0,1]
	v_add_u32_e32 v66, 0x80, v160
	v_pk_mul_f32 v[68:69], v[146:147], v[60:61] op_sel_hi:[0,1]
	v_pk_mul_f32 v[60:61], v[146:147], v[58:59] op_sel_hi:[0,1]
	v_mad_i64_i32 v[66:67], s[0:1], v66, s49, v[148:149]
	v_cvt_pk_bf16_f32 v58, v62, v63
	v_cvt_pk_bf16_f32 v59, v64, v65
	v_cvt_pk_bf16_f32 v60, v60, v61
	v_cvt_pk_bf16_f32 v61, v68, v69
	flat_store_dwordx4 v[66:67], v[58:61] sc1
	v_pk_mul_f32 v[52:53], v[146:147], v[52:53] op_sel_hi:[0,1]
	v_pk_mul_f32 v[50:51], v[146:147], v[50:51] op_sel_hi:[0,1]
	v_pk_mul_f32 v[58:59], v[146:147], v[44:45] op_sel_hi:[0,1]
	v_pk_mul_f32 v[44:45], v[146:147], v[42:43] op_sel_hi:[0,1]
	v_cvt_pk_bf16_f32 v42, v50, v51
	v_cvt_pk_bf16_f32 v43, v52, v53
	v_cvt_pk_bf16_f32 v44, v44, v45
	v_cvt_pk_bf16_f32 v45, v58, v59
	flat_store_dwordx4 v[66:67], v[42:45] offset:256 sc1
	v_pk_mul_f32 v[48:49], v[146:147], v[48:49] op_sel_hi:[0,1]
	v_pk_mul_f32 v[46:47], v[146:147], v[46:47] op_sel_hi:[0,1]
	v_add_u32_e32 v42, 0x90, v160
	v_pk_mul_f32 v[44:45], v[146:147], v[56:57] op_sel_hi:[0,1]
	v_mad_i64_i32 v[50:51], s[0:1], v42, s49, v[148:149]
	v_pk_mul_f32 v[42:43], v[146:147], v[54:55] op_sel_hi:[0,1]
	v_cvt_pk_bf16_f32 v42, v42, v43
	v_cvt_pk_bf16_f32 v43, v44, v45
	v_cvt_pk_bf16_f32 v44, v46, v47
	v_cvt_pk_bf16_f32 v45, v48, v49
	flat_store_dwordx4 v[50:51], v[42:45] sc1
	v_pk_mul_f32 v[36:37], v[146:147], v[36:37] op_sel_hi:[0,1]
	v_pk_mul_f32 v[34:35], v[146:147], v[34:35] op_sel_hi:[0,1]
	v_pk_mul_f32 v[42:43], v[146:147], v[28:29] op_sel_hi:[0,1]
	v_pk_mul_f32 v[28:29], v[146:147], v[26:27] op_sel_hi:[0,1]
	v_cvt_pk_bf16_f32 v26, v34, v35
	v_cvt_pk_bf16_f32 v27, v36, v37
	v_cvt_pk_bf16_f32 v28, v28, v29
	v_cvt_pk_bf16_f32 v29, v42, v43
	flat_store_dwordx4 v[50:51], v[26:29] offset:256 sc1
	v_pk_mul_f32 v[32:33], v[146:147], v[32:33] op_sel_hi:[0,1]
	v_pk_mul_f32 v[30:31], v[146:147], v[30:31] op_sel_hi:[0,1]
	v_add_u32_e32 v26, 0xa0, v160
	v_pk_mul_f32 v[28:29], v[146:147], v[40:41] op_sel_hi:[0,1]
	v_mad_i64_i32 v[34:35], s[0:1], v26, s49, v[148:149]
	v_pk_mul_f32 v[26:27], v[146:147], v[38:39] op_sel_hi:[0,1]
	v_cvt_pk_bf16_f32 v26, v26, v27
	v_cvt_pk_bf16_f32 v27, v28, v29
	v_cvt_pk_bf16_f32 v28, v30, v31
	v_cvt_pk_bf16_f32 v29, v32, v33
	flat_store_dwordx4 v[34:35], v[26:29] sc1
	v_pk_mul_f32 v[20:21], v[146:147], v[20:21] op_sel_hi:[0,1]
	v_pk_mul_f32 v[18:19], v[146:147], v[18:19] op_sel_hi:[0,1]
	v_pk_mul_f32 v[26:27], v[146:147], v[12:13] op_sel_hi:[0,1]
	v_pk_mul_f32 v[12:13], v[146:147], v[10:11] op_sel_hi:[0,1]
	v_cvt_pk_bf16_f32 v10, v18, v19
	v_cvt_pk_bf16_f32 v11, v20, v21
	v_cvt_pk_bf16_f32 v12, v12, v13
	v_cvt_pk_bf16_f32 v13, v26, v27
	flat_store_dwordx4 v[34:35], v[10:13] offset:256 sc1
	v_pk_mul_f32 v[16:17], v[146:147], v[16:17] op_sel_hi:[0,1]
	v_pk_mul_f32 v[14:15], v[146:147], v[14:15] op_sel_hi:[0,1]
	v_add_u32_e32 v10, 0xb0, v160
	v_pk_mul_f32 v[12:13], v[146:147], v[24:25] op_sel_hi:[0,1]
	v_mad_i64_i32 v[18:19], s[0:1], v10, s49, v[148:149]
	v_pk_mul_f32 v[10:11], v[146:147], v[22:23] op_sel_hi:[0,1]
	v_cvt_pk_bf16_f32 v10, v10, v11
	v_cvt_pk_bf16_f32 v11, v12, v13
	v_cvt_pk_bf16_f32 v12, v14, v15
	v_cvt_pk_bf16_f32 v13, v16, v17
	flat_store_dwordx4 v[18:19], v[10:13] sc1
	v_pk_mul_f32 v[8:9], v[146:147], v[8:9] op_sel_hi:[0,1]
	v_pk_mul_f32 v[6:7], v[146:147], v[6:7] op_sel_hi:[0,1]
	v_pk_mul_f32 v[10:11], v[146:147], v[4:5] op_sel_hi:[0,1]
	v_pk_mul_f32 v[4:5], v[146:147], v[2:3] op_sel_hi:[0,1]
	v_cvt_pk_bf16_f32 v2, v6, v7
	v_cvt_pk_bf16_f32 v3, v8, v9
	v_cvt_pk_bf16_f32 v4, v4, v5
	v_cvt_pk_bf16_f32 v5, v10, v11
	flat_store_dwordx4 v[18:19], v[2:5] offset:256 sc1
	s_branch .LBB0_891

.LBB0_1513:
	ds_read_b128 v[152:155], v149
	ds_read_b128 v[156:159], v149 offset:1024
	ds_read_b128 v[160:163], v149 offset:2048
	ds_read_b128 v[164:167], v149 offset:3072
	s_add_u32 s0, s26, 0xfffc0080
	s_addc_u32 s1, s27, -1
	s_cmp_eq_u32 s49, 12
	s_cselect_b32 s31, s21, s1
	s_cselect_b32 s30, s45, s0
	s_cselect_b32 s29, s19, s48
	s_cselect_b32 s28, s46, s47
	v_lshl_add_u64 v[200:201], s[26:27], 0, v[140:141]
	s_add_i32 m0, s10, 0xc000
	ds_read_b128 v[168:171], v150
	ds_read_b128 v[172:175], v150 offset:1024
	ds_read_b128 v[176:179], v150 offset:2048
	ds_read_b128 v[180:183], v150 offset:3072
	ds_read_b128 v[184:187], v150 offset:4096
	ds_read_b128 v[188:191], v150 offset:5120
	ds_read_b128 v[192:195], v150 offset:6144
	ds_read_b128 v[196:199], v150 offset:7168
	global_load_lds_dwordx4 v[200:201], off
	v_lshl_add_u64 v[200:201], s[26:27], 0, v[138:139]
	s_add_i32 m0, s10, 0xe000
	s_nop 0
	global_load_lds_dwordx4 v[200:201], off
	s_waitcnt lgkmcnt(8)
	s_waitcnt vmcnt(10)
	s_barrier
	s_waitcnt lgkmcnt(0)
	s_setprio 1
	s_waitcnt lgkmcnt(0)
	v_mfma_f32_16x16x32_bf16 v[126:129], v[152:155], v[168:171], v[126:129]
	v_mfma_f32_16x16x32_bf16 v[122:125], v[160:163], v[168:171], v[122:125]
	v_mfma_f32_16x16x32_bf16 v[118:121], v[152:155], v[176:179], v[118:121]
	v_mfma_f32_16x16x32_bf16 v[110:113], v[160:163], v[176:179], v[110:113]
	v_mfma_f32_16x16x32_bf16 v[102:105], v[152:155], v[184:187], v[102:105]
	v_mfma_f32_16x16x32_bf16 v[94:97], v[160:163], v[184:187], v[94:97]
	v_mfma_f32_16x16x32_bf16 v[86:89], v[152:155], v[192:195], v[86:89]
	v_mfma_f32_16x16x32_bf16 v[78:81], v[160:163], v[192:195], v[78:81]
	v_mfma_f32_16x16x32_bf16 v[126:129], v[156:159], v[172:175], v[126:129]
	v_mfma_f32_16x16x32_bf16 v[122:125], v[164:167], v[172:175], v[122:125]
	v_mfma_f32_16x16x32_bf16 v[118:121], v[156:159], v[180:183], v[118:121]
	v_mfma_f32_16x16x32_bf16 v[110:113], v[164:167], v[180:183], v[110:113]
	v_mfma_f32_16x16x32_bf16 v[102:105], v[156:159], v[188:191], v[102:105]
	v_mfma_f32_16x16x32_bf16 v[94:97], v[164:167], v[188:191], v[94:97]
	v_mfma_f32_16x16x32_bf16 v[86:89], v[156:159], v[196:199], v[86:89]
	v_mfma_f32_16x16x32_bf16 v[78:81], v[164:167], v[196:199], v[78:81]
	s_setprio 0
	s_barrier
	s_add_i32 s0, s42, s9
	v_lshl_add_u64 v[216:217], s[28:29], 0, v[134:135]
	s_mov_b32 m0, s0
	ds_read_b128 v[200:203], v151
	ds_read_b128 v[204:207], v151 offset:1024
	ds_read_b128 v[208:211], v151 offset:2048
	ds_read_b128 v[212:215], v151 offset:3072
	global_load_lds_dwordx4 v[216:217], off
	v_lshl_add_u64 v[218:219], s[28:29], 0, v[130:131]
	s_add_i32 m0, s0, 0x2000
	s_nop 0
	global_load_lds_dwordx4 v[218:219], off
	s_waitcnt vmcnt(10)
	s_barrier
	s_waitcnt lgkmcnt(0)
	s_setprio 1
	s_waitcnt lgkmcnt(0)
	v_mfma_f32_16x16x32_bf16 v[114:117], v[200:203], v[168:171], v[114:117]
	v_mfma_f32_16x16x32_bf16 v[106:109], v[208:211], v[168:171], v[106:109]
	v_mfma_f32_16x16x32_bf16 v[98:101], v[200:203], v[176:179], v[98:101]
	v_mfma_f32_16x16x32_bf16 v[90:93], v[208:211], v[176:179], v[90:93]
	v_mfma_f32_16x16x32_bf16 v[82:85], v[200:203], v[184:187], v[82:85]
	v_mfma_f32_16x16x32_bf16 v[74:77], v[208:211], v[184:187], v[74:77]
	v_mfma_f32_16x16x32_bf16 v[70:73], v[200:203], v[192:195], v[70:73]
	v_mfma_f32_16x16x32_bf16 v[66:69], v[208:211], v[192:195], v[66:69]
	v_mfma_f32_16x16x32_bf16 v[114:117], v[204:207], v[172:175], v[114:117]
	v_mfma_f32_16x16x32_bf16 v[106:109], v[212:215], v[172:175], v[106:109]
	v_mfma_f32_16x16x32_bf16 v[98:101], v[204:207], v[180:183], v[98:101]
	v_mfma_f32_16x16x32_bf16 v[90:93], v[212:215], v[180:183], v[90:93]
	v_mfma_f32_16x16x32_bf16 v[82:85], v[204:207], v[188:191], v[82:85]
	v_mfma_f32_16x16x32_bf16 v[74:77], v[212:215], v[188:191], v[74:77]
	v_mfma_f32_16x16x32_bf16 v[70:73], v[204:207], v[196:199], v[70:73]
	v_mfma_f32_16x16x32_bf16 v[66:69], v[212:215], v[196:199], v[66:69]
	s_setprio 0
	s_mov_b32 m0, s10
	v_lshl_add_u64 v[220:221], s[30:31], 0, v[136:137]
	s_barrier
	ds_read_b128 v[168:171], v150 offset:16384
	ds_read_b128 v[172:175], v150 offset:17408
	ds_read_b128 v[176:179], v150 offset:18432
	ds_read_b128 v[180:183], v150 offset:19456
	ds_read_b128 v[184:187], v150 offset:20480
	ds_read_b128 v[188:191], v150 offset:21504
	ds_read_b128 v[192:195], v150 offset:22528
	ds_read_b128 v[196:199], v150 offset:23552
	global_load_lds_dwordx4 v[220:221], off
	v_lshl_add_u64 v[222:223], s[30:31], 0, v[132:133]
	s_mov_b32 m0, s11
	s_nop 0
	global_load_lds_dwordx4 v[222:223], off
	s_waitcnt vmcnt(10)
	s_barrier
	s_waitcnt lgkmcnt(0)
	s_setprio 1
	s_waitcnt lgkmcnt(0)
	v_mfma_f32_16x16x32_bf16 v[62:65], v[152:155], v[168:171], v[62:65]
	v_mfma_f32_16x16x32_bf16 v[58:61], v[160:163], v[168:171], v[58:61]
	v_mfma_f32_16x16x32_bf16 v[54:57], v[152:155], v[176:179], v[54:57]
	v_mfma_f32_16x16x32_bf16 v[50:53], v[160:163], v[176:179], v[50:53]
	v_mfma_f32_16x16x32_bf16 v[38:41], v[152:155], v[184:187], v[38:41]
	v_mfma_f32_16x16x32_bf16 v[34:37], v[160:163], v[184:187], v[34:37]
	v_mfma_f32_16x16x32_bf16 v[22:25], v[152:155], v[192:195], v[22:25]
	v_mfma_f32_16x16x32_bf16 v[18:21], v[160:163], v[192:195], v[18:21]
	v_mfma_f32_16x16x32_bf16 v[62:65], v[156:159], v[172:175], v[62:65]
	v_mfma_f32_16x16x32_bf16 v[58:61], v[164:167], v[172:175], v[58:61]
	v_mfma_f32_16x16x32_bf16 v[54:57], v[156:159], v[180:183], v[54:57]
	v_mfma_f32_16x16x32_bf16 v[50:53], v[164:167], v[180:183], v[50:53]
	v_mfma_f32_16x16x32_bf16 v[38:41], v[156:159], v[188:191], v[38:41]
	v_mfma_f32_16x16x32_bf16 v[34:37], v[164:167], v[188:191], v[34:37]
	v_mfma_f32_16x16x32_bf16 v[22:25], v[156:159], v[196:199], v[22:25]
	v_mfma_f32_16x16x32_bf16 v[18:21], v[164:167], v[196:199], v[18:21]
	s_setprio 0
	s_barrier
	s_add_u32 s0, s28, 0x40000
	s_addc_u32 s1, s29, 0
	s_add_i32 s50, s43, s9
	v_lshl_add_u64 v[152:153], s[0:1], 0, v[134:135]
	s_mov_b32 m0, s50
	s_nop 0
	global_load_lds_dwordx4 v[152:153], off
	v_lshl_add_u64 v[152:153], s[0:1], 0, v[130:131]
	s_add_i32 m0, s50, 0x2000
	s_nop 0
	global_load_lds_dwordx4 v[152:153], off
	s_waitcnt vmcnt(10)
	s_barrier
	s_setprio 1
	v_mfma_f32_16x16x32_bf16 v[46:49], v[200:203], v[168:171], v[46:49]
	v_mfma_f32_16x16x32_bf16 v[42:45], v[208:211], v[168:171], v[42:45]
	v_mfma_f32_16x16x32_bf16 v[30:33], v[200:203], v[176:179], v[30:33]
	v_mfma_f32_16x16x32_bf16 v[26:29], v[208:211], v[176:179], v[26:29]
	v_mfma_f32_16x16x32_bf16 v[14:17], v[200:203], v[184:187], v[14:17]
	v_mfma_f32_16x16x32_bf16 v[10:13], v[208:211], v[184:187], v[10:13]
	v_mfma_f32_16x16x32_bf16 v[6:9], v[200:203], v[192:195], v[6:9]
	v_mfma_f32_16x16x32_bf16 v[2:5], v[208:211], v[192:195], v[2:5]
	v_mfma_f32_16x16x32_bf16 v[46:49], v[204:207], v[172:175], v[46:49]
	v_mfma_f32_16x16x32_bf16 v[42:45], v[212:215], v[172:175], v[42:45]
	v_mfma_f32_16x16x32_bf16 v[30:33], v[204:207], v[180:183], v[30:33]
	v_mfma_f32_16x16x32_bf16 v[26:29], v[212:215], v[180:183], v[26:29]
	v_mfma_f32_16x16x32_bf16 v[14:17], v[204:207], v[188:191], v[14:17]
	v_mfma_f32_16x16x32_bf16 v[10:13], v[212:215], v[188:191], v[10:13]
	v_mfma_f32_16x16x32_bf16 v[6:9], v[204:207], v[196:199], v[6:9]
	v_mfma_f32_16x16x32_bf16 v[2:5], v[212:215], v[196:199], v[2:5]
	s_setprio 0
	s_add_i32 s50, 0, 0x18000
	v_add_u32_e32 v164, s50, v148
	s_barrier
	ds_read_b128 v[152:155], v164
	ds_read_b128 v[156:159], v164 offset:1024
	ds_read_b128 v[160:163], v164 offset:2048
	ds_read_b128 v[164:167], v164 offset:3072
	s_add_u32 s0, s30, 0x40000
	s_addc_u32 s1, s31, 0
	s_mov_b32 m0, s17
	v_lshl_add_u64 v[200:201], s[0:1], 0, v[136:137]
	ds_read_b128 v[168:171], v150 offset:32768
	ds_read_b128 v[172:175], v150 offset:33792
	ds_read_b128 v[176:179], v150 offset:34816
	ds_read_b128 v[180:183], v150 offset:35840
	ds_read_b128 v[184:187], v150 offset:36864
	ds_read_b128 v[188:191], v150 offset:37888
	ds_read_b128 v[192:195], v150 offset:38912
	ds_read_b128 v[196:199], v150 offset:39936
	global_load_lds_dwordx4 v[200:201], off
	v_lshl_add_u64 v[200:201], s[0:1], 0, v[132:133]
	s_mov_b32 m0, s34
	s_nop 0
	global_load_lds_dwordx4 v[200:201], off
	s_waitcnt lgkmcnt(8)
	s_waitcnt vmcnt(10)
	s_barrier
	s_waitcnt lgkmcnt(0)
	s_setprio 1
	s_waitcnt lgkmcnt(0)
	v_mfma_f32_16x16x32_bf16 v[126:129], v[152:155], v[168:171], v[126:129]
	v_mfma_f32_16x16x32_bf16 v[122:125], v[160:163], v[168:171], v[122:125]
	v_mfma_f32_16x16x32_bf16 v[118:121], v[152:155], v[176:179], v[118:121]
	v_mfma_f32_16x16x32_bf16 v[110:113], v[160:163], v[176:179], v[110:113]
	v_mfma_f32_16x16x32_bf16 v[102:105], v[152:155], v[184:187], v[102:105]
	v_mfma_f32_16x16x32_bf16 v[94:97], v[160:163], v[184:187], v[94:97]
	v_mfma_f32_16x16x32_bf16 v[86:89], v[152:155], v[192:195], v[86:89]
	v_mfma_f32_16x16x32_bf16 v[78:81], v[160:163], v[192:195], v[78:81]
	v_mfma_f32_16x16x32_bf16 v[126:129], v[156:159], v[172:175], v[126:129]
	v_mfma_f32_16x16x32_bf16 v[122:125], v[164:167], v[172:175], v[122:125]
	v_mfma_f32_16x16x32_bf16 v[118:121], v[156:159], v[180:183], v[118:121]
	v_mfma_f32_16x16x32_bf16 v[110:113], v[164:167], v[180:183], v[110:113]
	v_mfma_f32_16x16x32_bf16 v[102:105], v[156:159], v[188:191], v[102:105]
	v_mfma_f32_16x16x32_bf16 v[94:97], v[164:167], v[188:191], v[94:97]
	v_mfma_f32_16x16x32_bf16 v[86:89], v[156:159], v[196:199], v[86:89]
	v_mfma_f32_16x16x32_bf16 v[78:81], v[164:167], v[196:199], v[78:81]
	s_setprio 0
	s_barrier
	s_add_i32 s30, 0, 0x1c000
	s_add_i32 s0, s50, s9
	v_add_u32_e32 v212, s30, v148
	v_lshl_add_u64 v[216:217], v[216:217], 0, s[14:15]
	s_mov_b32 m0, s0
	ds_read_b128 v[200:203], v212
	ds_read_b128 v[204:207], v212 offset:1024
	ds_read_b128 v[208:211], v212 offset:2048
	ds_read_b128 v[212:215], v212 offset:3072
	global_load_lds_dwordx4 v[216:217], off
	v_lshl_add_u64 v[216:217], v[218:219], 0, s[14:15]
	s_add_i32 m0, s0, 0x2000
	s_nop 0
	global_load_lds_dwordx4 v[216:217], off
	s_waitcnt vmcnt(10)
	s_barrier
	s_waitcnt lgkmcnt(0)
	s_setprio 1
	s_waitcnt lgkmcnt(0)
	v_mfma_f32_16x16x32_bf16 v[114:117], v[200:203], v[168:171], v[114:117]
	v_mfma_f32_16x16x32_bf16 v[106:109], v[208:211], v[168:171], v[106:109]
	v_mfma_f32_16x16x32_bf16 v[98:101], v[200:203], v[176:179], v[98:101]
	v_mfma_f32_16x16x32_bf16 v[90:93], v[208:211], v[176:179], v[90:93]
	v_mfma_f32_16x16x32_bf16 v[82:85], v[200:203], v[184:187], v[82:85]
	v_mfma_f32_16x16x32_bf16 v[74:77], v[208:211], v[184:187], v[74:77]
	v_mfma_f32_16x16x32_bf16 v[70:73], v[200:203], v[192:195], v[70:73]
	v_mfma_f32_16x16x32_bf16 v[66:69], v[208:211], v[192:195], v[66:69]
	v_mfma_f32_16x16x32_bf16 v[114:117], v[204:207], v[172:175], v[114:117]
	v_mfma_f32_16x16x32_bf16 v[106:109], v[212:215], v[172:175], v[106:109]
	v_mfma_f32_16x16x32_bf16 v[98:101], v[204:207], v[180:183], v[98:101]
	v_mfma_f32_16x16x32_bf16 v[90:93], v[212:215], v[180:183], v[90:93]
	v_mfma_f32_16x16x32_bf16 v[82:85], v[204:207], v[188:191], v[82:85]
	v_mfma_f32_16x16x32_bf16 v[74:77], v[212:215], v[188:191], v[74:77]
	v_mfma_f32_16x16x32_bf16 v[70:73], v[204:207], v[196:199], v[70:73]
	v_mfma_f32_16x16x32_bf16 v[66:69], v[212:215], v[196:199], v[66:69]
	s_setprio 0
	s_mov_b32 m0, s40
	v_lshl_add_u64 v[216:217], v[220:221], 0, s[14:15]
	s_barrier
	ds_read_b128 v[168:171], v150 offset:49152
	ds_read_b128 v[172:175], v150 offset:50176
	ds_read_b128 v[176:179], v150 offset:51200
	ds_read_b128 v[180:183], v150 offset:52224
	ds_read_b128 v[184:187], v150 offset:53248
	ds_read_b128 v[188:191], v150 offset:54272
	ds_read_b128 v[192:195], v150 offset:55296
	ds_read_b128 v[196:199], v150 offset:56320
	global_load_lds_dwordx4 v[216:217], off
	v_lshl_add_u64 v[216:217], v[222:223], 0, s[14:15]
	s_mov_b32 m0, s41
	s_nop 0
	global_load_lds_dwordx4 v[216:217], off
	s_waitcnt vmcnt(10)
	s_barrier
	s_waitcnt lgkmcnt(0)
	s_setprio 1
	s_waitcnt lgkmcnt(0)
	v_mfma_f32_16x16x32_bf16 v[62:65], v[152:155], v[168:171], v[62:65]
	v_mfma_f32_16x16x32_bf16 v[58:61], v[160:163], v[168:171], v[58:61]
	v_mfma_f32_16x16x32_bf16 v[54:57], v[152:155], v[176:179], v[54:57]
	v_mfma_f32_16x16x32_bf16 v[50:53], v[160:163], v[176:179], v[50:53]
	v_mfma_f32_16x16x32_bf16 v[38:41], v[152:155], v[184:187], v[38:41]
	v_mfma_f32_16x16x32_bf16 v[34:37], v[160:163], v[184:187], v[34:37]
	v_mfma_f32_16x16x32_bf16 v[22:25], v[152:155], v[192:195], v[22:25]
	v_mfma_f32_16x16x32_bf16 v[18:21], v[160:163], v[192:195], v[18:21]
	v_mfma_f32_16x16x32_bf16 v[62:65], v[156:159], v[172:175], v[62:65]
	v_mfma_f32_16x16x32_bf16 v[58:61], v[164:167], v[172:175], v[58:61]
	v_mfma_f32_16x16x32_bf16 v[54:57], v[156:159], v[180:183], v[54:57]
	v_mfma_f32_16x16x32_bf16 v[50:53], v[164:167], v[180:183], v[50:53]
	v_mfma_f32_16x16x32_bf16 v[38:41], v[156:159], v[188:191], v[38:41]
	v_mfma_f32_16x16x32_bf16 v[34:37], v[164:167], v[188:191], v[34:37]
	v_mfma_f32_16x16x32_bf16 v[22:25], v[156:159], v[196:199], v[22:25]
	v_mfma_f32_16x16x32_bf16 v[18:21], v[164:167], v[196:199], v[18:21]
	s_setprio 0
	s_barrier
	s_add_u32 s0, s28, 0x40080
	s_addc_u32 s1, s29, 0
	s_add_i32 s28, s30, s9
	v_lshl_add_u64 v[152:153], s[0:1], 0, v[134:135]
	s_mov_b32 m0, s28
	s_nop 0
	global_load_lds_dwordx4 v[152:153], off
	v_lshl_add_u64 v[152:153], s[0:1], 0, v[130:131]
	s_add_i32 m0, s28, 0x2000
	s_nop 0
	global_load_lds_dwordx4 v[152:153], off
	s_waitcnt vmcnt(10)
	s_barrier
	s_setprio 1
	v_mfma_f32_16x16x32_bf16 v[46:49], v[200:203], v[168:171], v[46:49]
	v_mfma_f32_16x16x32_bf16 v[42:45], v[208:211], v[168:171], v[42:45]
	v_mfma_f32_16x16x32_bf16 v[30:33], v[200:203], v[176:179], v[30:33]
	v_mfma_f32_16x16x32_bf16 v[26:29], v[208:211], v[176:179], v[26:29]
	v_mfma_f32_16x16x32_bf16 v[14:17], v[200:203], v[184:187], v[14:17]
	v_mfma_f32_16x16x32_bf16 v[10:13], v[208:211], v[184:187], v[10:13]
	v_mfma_f32_16x16x32_bf16 v[6:9], v[200:203], v[192:195], v[6:9]
	v_mfma_f32_16x16x32_bf16 v[2:5], v[208:211], v[192:195], v[2:5]
	v_mfma_f32_16x16x32_bf16 v[46:49], v[204:207], v[172:175], v[46:49]
	v_mfma_f32_16x16x32_bf16 v[42:45], v[212:215], v[172:175], v[42:45]
	v_mfma_f32_16x16x32_bf16 v[30:33], v[204:207], v[180:183], v[30:33]
	v_mfma_f32_16x16x32_bf16 v[26:29], v[212:215], v[180:183], v[26:29]
	v_mfma_f32_16x16x32_bf16 v[14:17], v[204:207], v[188:191], v[14:17]
	v_mfma_f32_16x16x32_bf16 v[10:13], v[212:215], v[188:191], v[10:13]
	v_mfma_f32_16x16x32_bf16 v[6:9], v[204:207], v[196:199], v[6:9]
	v_mfma_f32_16x16x32_bf16 v[2:5], v[212:215], v[196:199], v[2:5]
	s_setprio 0
	s_add_i32 s49, s49, 2
	s_add_u32 s47, s47, 0x100
	s_addc_u32 s48, s48, 0
	s_add_u32 s26, s26, 0x100
	s_addc_u32 s27, s27, 0
	s_cmp_gt_u32 s49, 13
	s_barrier
	s_cbranch_scc0 .LBB0_1513
	v_mov_b32_e32 v152, v146
	v_mov_b32_e32 v153, v147
	s_cmp_gt_i32 s44, 7
	s_cbranch_scc1 .LBB0_1505
	s_ashr_i32 s0, s44, 31
	s_lshr_b32 s0, s0, 30
	s_add_i32 s0, s44, s0
	s_ashr_i32 s0, s0, 2
	s_ashr_i32 s1, s0, 31
	s_lshl_b32 s19, s44, 8
	s_lshl_b64 s[26:27], s[0:1], 27
	s_add_u32 s26, s36, s26
	s_addc_u32 s27, s37, s27
	s_or_b32 s1, s19, s39
	s_lshl_b32 s0, s0, 10
	s_sub_i32 s0, s1, s0
	v_lshl_add_u32 v154, v153, 3, s0
	s_lshl_b32 s0, s16, 8
	s_add_i32 s0, s0, s38
	v_add_u32_e32 v156, s0, v152
	v_mov_b32_e32 v152, v156
	v_ashrrev_i32_e32 v155, 31, v154
	v_lshl_add_u64 v[154:155], v[154:155], 1, s[26:27]
	v_ashrrev_i32_e32 v153, 31, v152
	v_lshlrev_b64 v[152:153], 11, v[152:153]
	v_lshl_add_u64 v[152:153], v[154:155], 0, v[152:153]
	v_cvt_pk_bf16_f32 v126, v126, v127
	v_cvt_pk_bf16_f32 v127, v128, v129
	v_cvt_pk_bf16_f32 v128, v122, v123
	v_cvt_pk_bf16_f32 v129, v124, v125
	v_cvt_pk_bf16_f32 v114, v114, v115
	v_cvt_pk_bf16_f32 v115, v116, v117
	v_cvt_pk_bf16_f32 v116, v106, v107
	v_cvt_pk_bf16_f32 v117, v108, v109
	v_add_u32_e32 v106, 16, v156
	flat_store_dwordx4 v[152:153], v[126:129] sc1
	flat_store_dwordx4 v[152:153], v[114:117] offset:256 sc1
	v_cvt_pk_bf16_f32 v108, v110, v111
	v_ashrrev_i32_e32 v107, 31, v106
	v_lshlrev_b64 v[106:107], 11, v[106:107]
	v_lshl_add_u64 v[114:115], v[154:155], 0, v[106:107]
	v_cvt_pk_bf16_f32 v106, v118, v119
	v_cvt_pk_bf16_f32 v107, v120, v121
	v_cvt_pk_bf16_f32 v109, v112, v113
	v_cvt_pk_bf16_f32 v98, v98, v99
	v_cvt_pk_bf16_f32 v99, v100, v101
	v_cvt_pk_bf16_f32 v100, v90, v91
	v_cvt_pk_bf16_f32 v101, v92, v93
	v_add_u32_e32 v90, 32, v156
	flat_store_dwordx4 v[114:115], v[106:109] sc1
	flat_store_dwordx4 v[114:115], v[98:101] offset:256 sc1
	v_cvt_pk_bf16_f32 v92, v94, v95
	v_ashrrev_i32_e32 v91, 31, v90
	v_lshlrev_b64 v[90:91], 11, v[90:91]
	v_lshl_add_u64 v[98:99], v[154:155], 0, v[90:91]
	v_cvt_pk_bf16_f32 v90, v102, v103
	v_cvt_pk_bf16_f32 v91, v104, v105
	v_cvt_pk_bf16_f32 v93, v96, v97
	v_cvt_pk_bf16_f32 v82, v82, v83
	v_cvt_pk_bf16_f32 v83, v84, v85
	v_cvt_pk_bf16_f32 v84, v74, v75
	v_cvt_pk_bf16_f32 v85, v76, v77
	v_add_u32_e32 v74, 48, v156
	flat_store_dwordx4 v[98:99], v[90:93] sc1
	flat_store_dwordx4 v[98:99], v[82:85] offset:256 sc1
	v_cvt_pk_bf16_f32 v76, v78, v79
	v_ashrrev_i32_e32 v75, 31, v74
	v_lshlrev_b64 v[74:75], 11, v[74:75]
	v_lshl_add_u64 v[82:83], v[154:155], 0, v[74:75]
	v_cvt_pk_bf16_f32 v74, v86, v87
	v_cvt_pk_bf16_f32 v75, v88, v89
	v_cvt_pk_bf16_f32 v77, v80, v81
	v_cvt_pk_bf16_f32 v70, v70, v71
	v_cvt_pk_bf16_f32 v71, v72, v73
	v_cvt_pk_bf16_f32 v72, v66, v67
	v_cvt_pk_bf16_f32 v73, v68, v69
	v_add_u32_e32 v66, 0x80, v156
	flat_store_dwordx4 v[82:83], v[74:77] sc1
	flat_store_dwordx4 v[82:83], v[70:73] offset:256 sc1
	v_cvt_pk_bf16_f32 v62, v62, v63
	v_ashrrev_i32_e32 v67, 31, v66
	v_lshlrev_b64 v[66:67], 11, v[66:67]
	v_lshl_add_u64 v[66:67], v[154:155], 0, v[66:67]
	v_cvt_pk_bf16_f32 v63, v64, v65
	v_cvt_pk_bf16_f32 v64, v58, v59
	v_cvt_pk_bf16_f32 v65, v60, v61
	v_cvt_pk_bf16_f32 v46, v46, v47
	v_cvt_pk_bf16_f32 v47, v48, v49
	v_cvt_pk_bf16_f32 v48, v42, v43
	v_cvt_pk_bf16_f32 v49, v44, v45
	v_add_u32_e32 v42, 0x90, v156
	flat_store_dwordx4 v[66:67], v[62:65] sc1
	flat_store_dwordx4 v[66:67], v[46:49] offset:256 sc1
	v_cvt_pk_bf16_f32 v44, v50, v51
	v_ashrrev_i32_e32 v43, 31, v42
	v_lshlrev_b64 v[42:43], 11, v[42:43]
	v_lshl_add_u64 v[46:47], v[154:155], 0, v[42:43]
	v_cvt_pk_bf16_f32 v42, v54, v55
	v_cvt_pk_bf16_f32 v43, v56, v57
	v_cvt_pk_bf16_f32 v45, v52, v53
	v_cvt_pk_bf16_f32 v30, v30, v31
	v_cvt_pk_bf16_f32 v31, v32, v33
	v_cvt_pk_bf16_f32 v32, v26, v27
	v_cvt_pk_bf16_f32 v33, v28, v29
	v_add_u32_e32 v26, 0xa0, v156
	flat_store_dwordx4 v[46:47], v[42:45] sc1
	flat_store_dwordx4 v[46:47], v[30:33] offset:256 sc1
	v_cvt_pk_bf16_f32 v28, v34, v35
	v_ashrrev_i32_e32 v27, 31, v26
	v_lshlrev_b64 v[26:27], 11, v[26:27]
	v_lshl_add_u64 v[30:31], v[154:155], 0, v[26:27]
	v_cvt_pk_bf16_f32 v26, v38, v39
	v_cvt_pk_bf16_f32 v27, v40, v41
	v_cvt_pk_bf16_f32 v29, v36, v37
	v_cvt_pk_bf16_f32 v14, v14, v15
	v_cvt_pk_bf16_f32 v15, v16, v17
	v_cvt_pk_bf16_f32 v16, v10, v11
	v_cvt_pk_bf16_f32 v17, v12, v13
	v_add_u32_e32 v10, 0xb0, v156
	flat_store_dwordx4 v[30:31], v[26:29] sc1
	flat_store_dwordx4 v[30:31], v[14:17] offset:256 sc1
	v_cvt_pk_bf16_f32 v12, v18, v19
	v_ashrrev_i32_e32 v11, 31, v10
	v_lshlrev_b64 v[10:11], 11, v[10:11]
	v_lshl_add_u64 v[14:15], v[154:155], 0, v[10:11]
	v_cvt_pk_bf16_f32 v10, v22, v23
	v_cvt_pk_bf16_f32 v11, v24, v25
	v_cvt_pk_bf16_f32 v13, v20, v21
	v_cvt_pk_bf16_f32 v6, v6, v7
	v_cvt_pk_bf16_f32 v7, v8, v9
	v_cvt_pk_bf16_f32 v8, v2, v3
	v_cvt_pk_bf16_f32 v9, v4, v5
	flat_store_dwordx4 v[14:15], v[10:13] sc1
	flat_store_dwordx4 v[14:15], v[6:9] offset:256 sc1
	s_branch .LBB0_1505
